# v071 + 128-byte alignment of the eight hot loop heads (variant of v076)
# baseline (speedup 1.0000x reference)
.LBB0_351:
	s_ashr_i32 s17, s16, 31
	s_lshl_b64 s[24:25], s[16:17], 20
	s_add_u32 s24, s10, s24
	s_addc_u32 s25, s34, s25
	s_and_b64 s[30:31], s[40:41], exec
	s_cselect_b32 s17, s25, s43
	s_cselect_b32 s18, s24, s42
	s_ashr_i32 s5, s4, 31
	s_lshl_b64 s[30:31], s[4:5], 20
	s_add_u32 s30, s26, s30
	s_addc_u32 s31, s27, s31
	s_and_b64 s[52:53], s[40:41], exec
	s_cselect_b32 s5, s31, s45
	s_cselect_b32 s20, s30, s44
	s_add_u32 s42, s42, 0x80080
	s_addc_u32 s43, s43, 0
	s_add_u32 s28, s44, 0x100
	v_mov_b32_e32 v0, 0
	s_addc_u32 s33, s45, 0
	s_mov_b32 s54, -2
	v_mov_b32_e32 v1, v0
	v_mov_b32_e32 v2, v0
	v_mov_b32_e32 v3, v0
	v_mov_b32_e32 v4, v0
	v_mov_b32_e32 v5, v0
	v_mov_b32_e32 v6, v0
	v_mov_b32_e32 v7, v0
	v_mov_b32_e32 v16, v0
	v_mov_b32_e32 v17, v0
	v_mov_b32_e32 v18, v0
	v_mov_b32_e32 v19, v0
	v_mov_b32_e32 v20, v0
	v_mov_b32_e32 v21, v0
	v_mov_b32_e32 v22, v0
	v_mov_b32_e32 v23, v0
	v_mov_b32_e32 v32, v0
	v_mov_b32_e32 v33, v0
	v_mov_b32_e32 v34, v0
	v_mov_b32_e32 v35, v0
	v_mov_b32_e32 v36, v0
	v_mov_b32_e32 v37, v0
	v_mov_b32_e32 v38, v0
	v_mov_b32_e32 v39, v0
	v_mov_b32_e32 v48, v0
	v_mov_b32_e32 v49, v0
	v_mov_b32_e32 v50, v0
	v_mov_b32_e32 v51, v0
	v_mov_b32_e32 v52, v0
	v_mov_b32_e32 v53, v0
	v_mov_b32_e32 v54, v0
	v_mov_b32_e32 v55, v0
	v_mov_b32_e32 v8, v0
	v_mov_b32_e32 v9, v0
	v_mov_b32_e32 v10, v0
	v_mov_b32_e32 v11, v0
	v_mov_b32_e32 v12, v0
	v_mov_b32_e32 v13, v0
	v_mov_b32_e32 v14, v0
	v_mov_b32_e32 v15, v0
	v_mov_b32_e32 v24, v0
	v_mov_b32_e32 v25, v0
	v_mov_b32_e32 v26, v0
	v_mov_b32_e32 v27, v0
	v_mov_b32_e32 v28, v0
	v_mov_b32_e32 v29, v0
	v_mov_b32_e32 v30, v0
	v_mov_b32_e32 v31, v0
	v_mov_b32_e32 v40, v0
	v_mov_b32_e32 v41, v0
	v_mov_b32_e32 v42, v0
	v_mov_b32_e32 v43, v0
	v_mov_b32_e32 v44, v0
	v_mov_b32_e32 v45, v0
	v_mov_b32_e32 v46, v0
	v_mov_b32_e32 v47, v0
	v_mov_b32_e32 v56, v0
	v_mov_b32_e32 v57, v0
	v_mov_b32_e32 v58, v0
	v_mov_b32_e32 v59, v0
	v_mov_b32_e32 v60, v0
	v_mov_b32_e32 v61, v0
	v_mov_b32_e32 v62, v0
	v_mov_b32_e32 v63, v0
	v_mov_b32_e32 v64, v0
	v_mov_b32_e32 v65, v0
	v_mov_b32_e32 v66, v0
	v_mov_b32_e32 v67, v0
	v_mov_b32_e32 v68, v0
	v_mov_b32_e32 v69, v0
	v_mov_b32_e32 v70, v0
	v_mov_b32_e32 v71, v0
	v_mov_b32_e32 v80, v0
	v_mov_b32_e32 v81, v0
	v_mov_b32_e32 v82, v0
	v_mov_b32_e32 v83, v0
	v_mov_b32_e32 v84, v0
	v_mov_b32_e32 v85, v0
	v_mov_b32_e32 v86, v0
	v_mov_b32_e32 v87, v0
	v_mov_b32_e32 v98, v0
	v_mov_b32_e32 v99, v0
	v_mov_b32_e32 v100, v0
	v_mov_b32_e32 v101, v0
	v_mov_b32_e32 v102, v0
	v_mov_b32_e32 v103, v0
	v_mov_b32_e32 v104, v0
	v_mov_b32_e32 v105, v0
	v_mov_b32_e32 v114, v0
	v_mov_b32_e32 v115, v0
	v_mov_b32_e32 v116, v0
	v_mov_b32_e32 v117, v0
	v_mov_b32_e32 v118, v0
	v_mov_b32_e32 v119, v0
	v_mov_b32_e32 v120, v0
	v_mov_b32_e32 v121, v0
	v_mov_b32_e32 v72, v0
	v_mov_b32_e32 v73, v0
	v_mov_b32_e32 v74, v0
	v_mov_b32_e32 v75, v0
	v_mov_b32_e32 v76, v0
	v_mov_b32_e32 v77, v0
	v_mov_b32_e32 v78, v0
	v_mov_b32_e32 v79, v0
	v_mov_b32_e32 v88, v0
	v_mov_b32_e32 v89, v0
	v_mov_b32_e32 v90, v0
	v_mov_b32_e32 v91, v0
	v_mov_b32_e32 v92, v0
	v_mov_b32_e32 v93, v0
	v_mov_b32_e32 v94, v0
	v_mov_b32_e32 v95, v0
	v_mov_b32_e32 v106, v0
	v_mov_b32_e32 v107, v0
	v_mov_b32_e32 v108, v0
	v_mov_b32_e32 v109, v0
	v_mov_b32_e32 v110, v0
	v_mov_b32_e32 v111, v0
	v_mov_b32_e32 v112, v0
	v_mov_b32_e32 v113, v0
	v_mov_b32_e32 v122, v0
	v_mov_b32_e32 v123, v0
	v_mov_b32_e32 v124, v0
	v_mov_b32_e32 v125, v0
	v_mov_b32_e32 v126, v0
	v_mov_b32_e32 v127, v0
	v_mov_b32_e32 v128, v0
	v_mov_b32_e32 v129, v0
	v_add_u32_e32 v154, 0x80, v142
	v_add_u32_e32 v155, 0x80, v138
	v_add_u32_e32 v156, 0x80, v144
	v_add_u32_e32 v157, 0x80, v140
	v_add_u32_e32 v202, 0x80000, v144
	v_add_u32_e32 v203, 0x80000, v140
	.p2align 7

.LBB0_635:
	s_ashr_i32 s43, s42, 31
	s_lshl_b64 s[44:45], s[42:43], 18
	s_add_u32 s44, s2, s44
	s_addc_u32 s45, s3, s45
	s_and_b64 s[50:51], s[40:41], exec
	s_cselect_b32 s35, s45, s69
	s_cselect_b32 s43, s44, s68
	s_ashr_i32 s31, s30, 31
	s_lshl_b64 s[50:51], s[30:31], 18
	s_add_u32 s52, s16, s50
	s_addc_u32 s53, s17, s51
	s_and_b64 s[50:51], s[40:41], exec
	s_cselect_b32 s31, s53, s83
	s_cselect_b32 s50, s52, s82
	s_add_u32 s68, s68, 0x20080
	s_addc_u32 s69, s69, 0
	s_add_u32 s51, s82, 0x100
	v_mov_b32_e32 v0, 0
	s_addc_u32 s54, s83, 0
	s_mov_b32 s55, -2
	v_mov_b32_e32 v1, v0
	v_mov_b32_e32 v2, v0
	v_mov_b32_e32 v3, v0
	v_mov_b32_e32 v4, v0
	v_mov_b32_e32 v5, v0
	v_mov_b32_e32 v6, v0
	v_mov_b32_e32 v7, v0
	v_mov_b32_e32 v8, v0
	v_mov_b32_e32 v9, v0
	v_mov_b32_e32 v10, v0
	v_mov_b32_e32 v11, v0
	v_mov_b32_e32 v12, v0
	v_mov_b32_e32 v13, v0
	v_mov_b32_e32 v14, v0
	v_mov_b32_e32 v15, v0
	v_mov_b32_e32 v24, v0
	v_mov_b32_e32 v25, v0
	v_mov_b32_e32 v26, v0
	v_mov_b32_e32 v27, v0
	v_mov_b32_e32 v28, v0
	v_mov_b32_e32 v29, v0
	v_mov_b32_e32 v30, v0
	v_mov_b32_e32 v31, v0
	v_mov_b32_e32 v40, v0
	v_mov_b32_e32 v41, v0
	v_mov_b32_e32 v42, v0
	v_mov_b32_e32 v43, v0
	v_mov_b32_e32 v44, v0
	v_mov_b32_e32 v45, v0
	v_mov_b32_e32 v46, v0
	v_mov_b32_e32 v47, v0
	v_mov_b32_e32 v16, v0
	v_mov_b32_e32 v17, v0
	v_mov_b32_e32 v18, v0
	v_mov_b32_e32 v19, v0
	v_mov_b32_e32 v20, v0
	v_mov_b32_e32 v21, v0
	v_mov_b32_e32 v22, v0
	v_mov_b32_e32 v23, v0
	v_mov_b32_e32 v32, v0
	v_mov_b32_e32 v33, v0
	v_mov_b32_e32 v34, v0
	v_mov_b32_e32 v35, v0
	v_mov_b32_e32 v36, v0
	v_mov_b32_e32 v37, v0
	v_mov_b32_e32 v38, v0
	v_mov_b32_e32 v39, v0
	v_mov_b32_e32 v48, v0
	v_mov_b32_e32 v49, v0
	v_mov_b32_e32 v50, v0
	v_mov_b32_e32 v51, v0
	v_mov_b32_e32 v52, v0
	v_mov_b32_e32 v53, v0
	v_mov_b32_e32 v54, v0
	v_mov_b32_e32 v55, v0
	v_mov_b32_e32 v56, v0
	v_mov_b32_e32 v57, v0
	v_mov_b32_e32 v58, v0
	v_mov_b32_e32 v59, v0
	v_mov_b32_e32 v60, v0
	v_mov_b32_e32 v61, v0
	v_mov_b32_e32 v62, v0
	v_mov_b32_e32 v63, v0
	v_mov_b32_e32 v64, v0
	v_mov_b32_e32 v65, v0
	v_mov_b32_e32 v66, v0
	v_mov_b32_e32 v67, v0
	v_mov_b32_e32 v68, v0
	v_mov_b32_e32 v69, v0
	v_mov_b32_e32 v70, v0
	v_mov_b32_e32 v71, v0
	v_mov_b32_e32 v72, v0
	v_mov_b32_e32 v73, v0
	v_mov_b32_e32 v74, v0
	v_mov_b32_e32 v75, v0
	v_mov_b32_e32 v76, v0
	v_mov_b32_e32 v77, v0
	v_mov_b32_e32 v78, v0
	v_mov_b32_e32 v79, v0
	v_mov_b32_e32 v88, v0
	v_mov_b32_e32 v89, v0
	v_mov_b32_e32 v90, v0
	v_mov_b32_e32 v91, v0
	v_mov_b32_e32 v92, v0
	v_mov_b32_e32 v93, v0
	v_mov_b32_e32 v94, v0
	v_mov_b32_e32 v95, v0
	v_mov_b32_e32 v106, v0
	v_mov_b32_e32 v107, v0
	v_mov_b32_e32 v108, v0
	v_mov_b32_e32 v109, v0
	v_mov_b32_e32 v110, v0
	v_mov_b32_e32 v111, v0
	v_mov_b32_e32 v112, v0
	v_mov_b32_e32 v113, v0
	v_mov_b32_e32 v80, v0
	v_mov_b32_e32 v81, v0
	v_mov_b32_e32 v82, v0
	v_mov_b32_e32 v83, v0
	v_mov_b32_e32 v84, v0
	v_mov_b32_e32 v85, v0
	v_mov_b32_e32 v86, v0
	v_mov_b32_e32 v87, v0
	v_mov_b32_e32 v98, v0
	v_mov_b32_e32 v99, v0
	v_mov_b32_e32 v100, v0
	v_mov_b32_e32 v101, v0
	v_mov_b32_e32 v102, v0
	v_mov_b32_e32 v103, v0
	v_mov_b32_e32 v104, v0
	v_mov_b32_e32 v105, v0
	v_mov_b32_e32 v114, v0
	v_mov_b32_e32 v115, v0
	v_mov_b32_e32 v116, v0
	v_mov_b32_e32 v117, v0
	v_mov_b32_e32 v118, v0
	v_mov_b32_e32 v119, v0
	v_mov_b32_e32 v120, v0
	v_mov_b32_e32 v121, v0
	v_mov_b32_e32 v122, v0
	v_mov_b32_e32 v123, v0
	v_mov_b32_e32 v124, v0
	v_mov_b32_e32 v125, v0
	v_mov_b32_e32 v126, v0
	v_mov_b32_e32 v127, v0
	v_mov_b32_e32 v128, v0
	v_mov_b32_e32 v129, v0
	v_add_u32_e32 v155, 0x80, v96
	v_add_u32_e32 v157, 0x80, v130
	v_add_u32_e32 v199, 0x80, v134
	v_add_u32_e32 v203, 0x80, v132
	.p2align 7

.LBB0_655:
	s_ashr_i32 s43, s42, 31
	s_lshl_b64 s[44:45], s[42:43], 18
	s_add_u32 s44, s10, s44
	s_addc_u32 s45, s12, s45
	s_and_b64 s[52:53], s[40:41], exec
	s_cselect_b32 s43, s45, s69
	s_cselect_b32 s51, s44, s68
	s_ashr_i32 s31, s30, 31
	s_lshl_b64 s[52:53], s[30:31], 18
	s_add_u32 s52, s2, s52
	s_addc_u32 s53, s3, s53
	s_and_b64 s[54:55], s[40:41], exec
	s_cselect_b32 s31, s53, s83
	s_cselect_b32 s54, s52, s82
	s_add_u32 s68, s68, 0x20080
	s_addc_u32 s69, s69, 0
	s_add_u32 s55, s82, 0x100
	v_mov_b32_e32 v0, 0
	s_addc_u32 s56, s83, 0
	s_mov_b32 s57, -2
	v_mov_b32_e32 v1, v0
	v_mov_b32_e32 v2, v0
	v_mov_b32_e32 v3, v0
	v_mov_b32_e32 v4, v0
	v_mov_b32_e32 v5, v0
	v_mov_b32_e32 v6, v0
	v_mov_b32_e32 v7, v0
	v_mov_b32_e32 v8, v0
	v_mov_b32_e32 v9, v0
	v_mov_b32_e32 v10, v0
	v_mov_b32_e32 v11, v0
	v_mov_b32_e32 v12, v0
	v_mov_b32_e32 v13, v0
	v_mov_b32_e32 v14, v0
	v_mov_b32_e32 v15, v0
	v_mov_b32_e32 v24, v0
	v_mov_b32_e32 v25, v0
	v_mov_b32_e32 v26, v0
	v_mov_b32_e32 v27, v0
	v_mov_b32_e32 v28, v0
	v_mov_b32_e32 v29, v0
	v_mov_b32_e32 v30, v0
	v_mov_b32_e32 v31, v0
	v_mov_b32_e32 v40, v0
	v_mov_b32_e32 v41, v0
	v_mov_b32_e32 v42, v0
	v_mov_b32_e32 v43, v0
	v_mov_b32_e32 v44, v0
	v_mov_b32_e32 v45, v0
	v_mov_b32_e32 v46, v0
	v_mov_b32_e32 v47, v0
	v_mov_b32_e32 v16, v0
	v_mov_b32_e32 v17, v0
	v_mov_b32_e32 v18, v0
	v_mov_b32_e32 v19, v0
	v_mov_b32_e32 v20, v0
	v_mov_b32_e32 v21, v0
	v_mov_b32_e32 v22, v0
	v_mov_b32_e32 v23, v0
	v_mov_b32_e32 v32, v0
	v_mov_b32_e32 v33, v0
	v_mov_b32_e32 v34, v0
	v_mov_b32_e32 v35, v0
	v_mov_b32_e32 v36, v0
	v_mov_b32_e32 v37, v0
	v_mov_b32_e32 v38, v0
	v_mov_b32_e32 v39, v0
	v_mov_b32_e32 v48, v0
	v_mov_b32_e32 v49, v0
	v_mov_b32_e32 v50, v0
	v_mov_b32_e32 v51, v0
	v_mov_b32_e32 v52, v0
	v_mov_b32_e32 v53, v0
	v_mov_b32_e32 v54, v0
	v_mov_b32_e32 v55, v0
	v_mov_b32_e32 v56, v0
	v_mov_b32_e32 v57, v0
	v_mov_b32_e32 v58, v0
	v_mov_b32_e32 v59, v0
	v_mov_b32_e32 v60, v0
	v_mov_b32_e32 v61, v0
	v_mov_b32_e32 v62, v0
	v_mov_b32_e32 v63, v0
	v_mov_b32_e32 v64, v0
	v_mov_b32_e32 v65, v0
	v_mov_b32_e32 v66, v0
	v_mov_b32_e32 v67, v0
	v_mov_b32_e32 v68, v0
	v_mov_b32_e32 v69, v0
	v_mov_b32_e32 v70, v0
	v_mov_b32_e32 v71, v0
	v_mov_b32_e32 v72, v0
	v_mov_b32_e32 v73, v0
	v_mov_b32_e32 v74, v0
	v_mov_b32_e32 v75, v0
	v_mov_b32_e32 v76, v0
	v_mov_b32_e32 v77, v0
	v_mov_b32_e32 v78, v0
	v_mov_b32_e32 v79, v0
	v_mov_b32_e32 v88, v0
	v_mov_b32_e32 v89, v0
	v_mov_b32_e32 v90, v0
	v_mov_b32_e32 v91, v0
	v_mov_b32_e32 v92, v0
	v_mov_b32_e32 v93, v0
	v_mov_b32_e32 v94, v0
	v_mov_b32_e32 v95, v0
	v_mov_b32_e32 v106, v0
	v_mov_b32_e32 v107, v0
	v_mov_b32_e32 v108, v0
	v_mov_b32_e32 v109, v0
	v_mov_b32_e32 v110, v0
	v_mov_b32_e32 v111, v0
	v_mov_b32_e32 v112, v0
	v_mov_b32_e32 v113, v0
	v_mov_b32_e32 v80, v0
	v_mov_b32_e32 v81, v0
	v_mov_b32_e32 v82, v0
	v_mov_b32_e32 v83, v0
	v_mov_b32_e32 v84, v0
	v_mov_b32_e32 v85, v0
	v_mov_b32_e32 v86, v0
	v_mov_b32_e32 v87, v0
	v_mov_b32_e32 v98, v0
	v_mov_b32_e32 v99, v0
	v_mov_b32_e32 v100, v0
	v_mov_b32_e32 v101, v0
	v_mov_b32_e32 v102, v0
	v_mov_b32_e32 v103, v0
	v_mov_b32_e32 v104, v0
	v_mov_b32_e32 v105, v0
	v_mov_b32_e32 v114, v0
	v_mov_b32_e32 v115, v0
	v_mov_b32_e32 v116, v0
	v_mov_b32_e32 v117, v0
	v_mov_b32_e32 v118, v0
	v_mov_b32_e32 v119, v0
	v_mov_b32_e32 v120, v0
	v_mov_b32_e32 v121, v0
	v_mov_b32_e32 v122, v0
	v_mov_b32_e32 v123, v0
	v_mov_b32_e32 v124, v0
	v_mov_b32_e32 v125, v0
	v_mov_b32_e32 v126, v0
	v_mov_b32_e32 v127, v0
	v_mov_b32_e32 v128, v0
	v_mov_b32_e32 v129, v0
	v_add_u32_e32 v155, 0x80, v96
	v_add_u32_e32 v157, 0x80, v130
	v_add_u32_e32 v199, 0x80, v134
	v_add_u32_e32 v203, 0x80, v132
	.p2align 7

.LBB0_735:
	s_mov_b32 s68, s78
	s_mov_b64 s[0:1], 0
	v_mbcnt_lo_u32_b32 v137, -1, 0
	v_mbcnt_hi_u32_b32 v137, -1, v137
	s_add_u32 s40, s62, s0
	s_addc_u32 s41, s63, s1
	s_add_u32 s24, s40, 0x2f800000
	s_addc_u32 s25, s41, 0
	s_add_u32 s52, s40, 0x800000
	s_addc_u32 s53, s41, 0
	s_add_u32 s4, s40, 0x880000
	s_addc_u32 s5, s41, 0
	v_sub_co_u32_e64 v0, s[2:3], s42, 1
	s_and_b64 s[2:3], s[2:3], exec
	v_readfirstlane_b32 s2, v0
	s_cselect_b32 s10, 2, s2
	s_and_b64 s[2:3], s[34:35], exec
	s_cselect_b32 s2, s42, s10
	s_cmp_lg_u32 s2, 2
	s_mov_b64 s[16:17], -1
	s_cbranch_scc0 .LBB0_761
	s_andn2_b64 vcc, exec, s[54:55]
	s_cbranch_vccnz .LBB0_760
	s_cmp_eq_u32 s2, 0
	s_cselect_b32 s2, s15, s9
	s_lshl_b32 s14, s2, 8
	v_mbcnt_lo_u32_b32 v56, -1, 0
	v_mbcnt_hi_u32_b32 v56, -1, v56
	s_add_i32 s3, s14, s13
	v_and_b32_e32 v158, 31, v56
	v_or_b32_e32 v96, s3, v158
	v_lshl_add_u64 v[16:17], s[36:37], 0, v[96:97]
	v_mov_b64_e32 v[18:19], s[40:41]
	s_movk_i32 s3, 0xc00
	v_mad_u64_u32 v[18:19], s[16:17], v16, s3, v[18:19]
	v_readlane_b32 s16, v253, 43
	v_readlane_b32 s17, v253, 44
	v_bfe_u32 v159, v56, 5, 1
	v_mad_i32_i24 v19, v17, s3, v19
	s_mov_b32 s17, s80
	v_lshlrev_b64 v[0:1], 7, v[96:97]
	v_lshl_add_u64 v[16:17], v[18:19], 0, s[16:17]
	v_lshlrev_b32_e32 v130, 4, v159
	v_mov_b32_e32 v131, v97
	v_lshl_add_u64 v[2:3], s[52:53], 0, v[0:1]
	v_and_b32_e32 v96, 32, v56
	s_mov_b32 s10, s16
	v_lshl_add_u64 v[26:27], v[16:17], 0, v[130:131]
	s_mov_b64 s[16:17], 0x2ff00000
	v_lshl_add_u64 v[24:25], v[2:3], 0, v[96:97]
	v_lshl_add_u64 v[0:1], s[4:5], 0, v[0:1]
	v_lshl_add_u64 v[30:31], v[26:27], 0, s[16:17]
	v_lshl_add_u64 v[28:29], v[0:1], 0, v[96:97]
	global_load_dwordx4 v[0:3], v[24:25], off
	global_load_dwordx4 v[4:7], v[28:29], off
	global_load_dwordx4 v[8:11], v[24:25], off offset:16
	global_load_dwordx4 v[12:15], v[28:29], off offset:16
	global_load_dwordx4 v[16:19], v[30:31], off offset:320
	global_load_dwordx4 v[20:23], v[30:31], off offset:256
	s_mov_b32 s3, 0x2ff00000
	v_add_co_u32_e32 v26, vcc, s3, v26
	v_and_b32_e32 v131, 63, v56
	s_nop 0
	v_addc_co_u32_e32 v27, vcc, 0, v27, vcc
	global_load_dwordx4 v[126:129], v[26:27], off
	global_load_dwordx4 v[98:101], v[30:31], off offset:224
	global_load_dwordx4 v[122:125], v[30:31], off offset:32
	global_load_dwordx4 v[118:121], v[30:31], off offset:64
	global_load_dwordx4 v[114:117], v[30:31], off offset:96
	global_load_dwordx4 v[110:113], v[30:31], off offset:128
	global_load_dwordx4 v[106:109], v[30:31], off offset:160
	global_load_dwordx4 v[102:105], v[30:31], off offset:192
	v_lshlrev_b32_e32 v57, 4, v131
	v_add_u32_e32 v163, s20, v57
	v_writelane_b32 v253, s10, 43
	s_add_u32 s3, s40, s46
	v_or_b32_e32 v58, 32, v130
	v_writelane_b32 v253, s11, 44
	s_addc_u32 s10, s41, s47
	v_readlane_b32 s12, v253, 38
	s_add_u32 s3, s3, s12
	s_addc_u32 s10, s10, 0
	s_add_u32 s16, s3, 0x33000000
	s_addc_u32 s17, s10, 0
	v_or_b32_e32 v59, 64, v130
	v_or_b32_e32 v62, 0x60, v130
	v_lshlrev_b32_e32 v63, 7, v158
	s_mov_b32 s81, s80
	s_mov_b32 s82, s80
	s_mov_b32 s83, s80
	s_mov_b32 s84, s80
	s_mov_b32 s85, s80
	s_mov_b32 s86, s80
	s_mov_b32 s87, s80
	s_mov_b32 s88, s80
	s_mov_b32 s89, s80
	s_mov_b32 s90, s80
	s_mov_b32 s91, s80
	s_mov_b32 s92, s80
	s_mov_b32 s93, s80
	s_mov_b32 s94, s80
	s_mov_b32 s95, s80
	s_mov_b32 s26, 2
	v_cmp_gt_u32_e64 s[38:39], 32, v131
	v_lshl_add_u32 v160, v158, 2, s19
	v_mov_b32_e32 v161, 0
	s_waitcnt vmcnt(13)
	v_mov_b32_e32 v33, v0
	s_waitcnt vmcnt(12)
	v_mov_b32_e32 v27, v4
	v_mov_b32_e32 v32, v4
	v_mov_b32_e32 v4, v1
	s_waitcnt vmcnt(9)
	v_lshlrev_b32_e32 v43, 16, v16
	s_waitcnt vmcnt(8)
	v_lshlrev_b32_e32 v42, 16, v20
	v_and_b32_e32 v45, 0xffff0000, v16
	v_and_b32_e32 v44, 0xffff0000, v20
	v_mov_b32_e32 v26, v0
	v_mov_b32_e32 v0, v5
	v_mov_b32_e32 v34, v2
	v_mov_b32_e32 v35, v6
	v_mov_b32_e32 v37, v2
	v_mov_b32_e32 v2, v7
	v_lshlrev_b32_e32 v47, 16, v17
	v_lshlrev_b32_e32 v46, 16, v21
	v_and_b32_e32 v17, 0xffff0000, v17
	v_and_b32_e32 v16, 0xffff0000, v21
	v_pk_mul_f32 v[32:33], v[32:33], v[42:43]
	v_pk_mul_f32 v[4:5], v[4:5], v[44:45]
	v_mov_b32_e32 v36, v6
	v_mov_b32_e32 v6, v3
	v_mov_b32_e32 v39, v12
	v_mov_b32_e32 v40, v12
	v_pk_mul_f32 v[26:27], v[26:27], v[42:43]
	v_pk_mul_f32 v[0:1], v[0:1], v[44:45]
	v_pk_mul_f32 v[34:35], v[34:35], v[46:47]
	v_pk_mul_f32 v[2:3], v[2:3], v[16:17]
	v_add_f32_e32 v12, v32, v33
	v_sub_f32_e32 v4, v4, v5
	v_mov_b32_e32 v38, v8
	v_mov_b32_e32 v41, v8
	v_lshlrev_b32_e32 v21, 16, v18
	v_lshlrev_b32_e32 v20, 16, v22
	v_and_b32_e32 v49, 0xffff0000, v18
	v_and_b32_e32 v48, 0xffff0000, v22
	v_pk_mul_f32 v[36:37], v[36:37], v[46:47]
	v_pk_mul_f32 v[6:7], v[6:7], v[16:17]
	v_sub_f32_e32 v8, v26, v27
	v_add_f32_e32 v1, v0, v1
	v_sub_f32_e32 v5, v34, v35
	v_add_f32_e32 v2, v2, v3
	v_cvt_pk_bf16_f32 v0, v8, v4
	v_cvt_pk_bf16_f32 v4, v12, v1
	v_mov_b32_e32 v12, v9
	v_pk_mul_f32 v[16:17], v[38:39], v[20:21]
	v_add_f32_e32 v18, v36, v37
	v_sub_f32_e32 v6, v6, v7
	v_cvt_pk_bf16_f32 v1, v5, v6
	v_cvt_pk_bf16_f32 v5, v18, v2
	v_pk_mul_f32 v[2:3], v[12:13], v[48:49]
	v_sub_f32_e32 v7, v16, v17
	v_sub_f32_e32 v2, v2, v3
	v_mov_b32_e32 v8, v13
	v_cvt_pk_bf16_f32 v2, v7, v2
	v_pk_mul_f32 v[6:7], v[8:9], v[48:49]
	v_lshlrev_b32_e32 v9, 16, v19
	v_lshlrev_b32_e32 v8, 16, v23
	v_mov_b32_e32 v12, v10
	v_mov_b32_e32 v13, v14
	v_pk_mul_f32 v[20:21], v[40:41], v[20:21]
	v_add_f32_e32 v3, v6, v7
	v_pk_mul_f32 v[12:13], v[12:13], v[8:9]
	v_add_f32_e32 v16, v20, v21
	v_cvt_pk_bf16_f32 v6, v16, v3
	v_sub_f32_e32 v3, v12, v13
	v_mov_b32_e32 v12, v14
	v_mov_b32_e32 v13, v10
	v_pk_mul_f32 v[8:9], v[12:13], v[8:9]
	v_mov_b32_e32 v14, v11
	v_add_f32_e32 v7, v8, v9
	v_and_b32_e32 v9, 0xffff0000, v19
	v_and_b32_e32 v8, 0xffff0000, v23
	v_pk_mul_f32 v[12:13], v[14:15], v[8:9]
	v_add_u32_e32 v40, s18, v56
	v_sub_f32_e32 v10, v12, v13
	v_cvt_pk_bf16_f32 v3, v3, v10
	v_mov_b32_e32 v10, v15
	v_pk_mul_f32 v[8:9], v[10:11], v[8:9]
	s_nop 0
	v_add_f32_e32 v8, v8, v9
	v_cvt_pk_bf16_f32 v7, v7, v8
	global_load_dwordx4 v[8:11], v[30:31], off offset:352
	global_load_dwordx4 v[12:15], v[30:31], off offset:288
	global_load_dwordx4 v[16:19], v[24:25], off offset:64
	global_load_dwordx4 v[20:23], v[28:29], off offset:64
	s_nop 0
	global_load_dwordx4 v[24:27], v[24:25], off offset:80
	s_nop 0
	global_load_dwordx4 v[28:31], v[28:29], off offset:80
	ds_write_b128 v163, v[0:3]
	ds_write_b128 v163, v[4:7] offset:2048
	s_waitcnt vmcnt(5)
	v_lshlrev_b32_e32 v1, 16, v8
	s_waitcnt vmcnt(4)
	v_lshlrev_b32_e32 v0, 16, v12
	s_waitcnt vmcnt(3)
	v_mov_b32_e32 v2, v16
	s_waitcnt vmcnt(2)
	v_mov_b32_e32 v3, v20
	v_mov_b32_e32 v4, v20
	v_mov_b32_e32 v5, v16
	v_and_b32_e32 v7, 0xffff0000, v8
	v_and_b32_e32 v6, 0xffff0000, v12
	v_mov_b32_e32 v20, v17
	v_mov_b32_e32 v16, v21
	v_lshlrev_b32_e32 v33, 16, v9
	v_lshlrev_b32_e32 v32, 16, v13
	v_mov_b32_e32 v34, v18
	v_mov_b32_e32 v35, v22
	v_mov_b32_e32 v36, v22
	v_mov_b32_e32 v37, v18
	v_and_b32_e32 v9, 0xffff0000, v9
	v_and_b32_e32 v8, 0xffff0000, v13
	v_mov_b32_e32 v22, v19
	v_mov_b32_e32 v18, v23
	v_pk_mul_f32 v[2:3], v[2:3], v[0:1]
	v_pk_mul_f32 v[0:1], v[4:5], v[0:1]
	v_pk_mul_f32 v[4:5], v[20:21], v[6:7]
	v_pk_mul_f32 v[6:7], v[16:17], v[6:7]
	v_lshlrev_b32_e32 v13, 16, v10
	v_lshlrev_b32_e32 v12, 16, v14
	s_waitcnt vmcnt(1)
	v_mov_b32_e32 v38, v24
	v_pk_mul_f32 v[16:17], v[34:35], v[32:33]
	v_pk_mul_f32 v[22:23], v[22:23], v[8:9]
	v_pk_mul_f32 v[8:9], v[18:19], v[8:9]
	v_sub_f32_e32 v2, v2, v3
	v_add_f32_e32 v1, v0, v1
	v_sub_f32_e32 v0, v4, v5
	v_add_f32_e32 v3, v6, v7
	s_waitcnt vmcnt(0)
	v_mov_b32_e32 v39, v28
	v_pk_mul_f32 v[20:21], v[36:37], v[32:33]
	v_sub_f32_e32 v5, v16, v17
	v_add_f32_e32 v8, v8, v9
	v_cvt_pk_bf16_f32 v0, v2, v0
	v_cvt_pk_bf16_f32 v4, v1, v3
	v_pk_mul_f32 v[2:3], v[38:39], v[12:13]
	v_add_f32_e32 v6, v20, v21
	v_sub_f32_e32 v7, v22, v23
	v_cvt_pk_bf16_f32 v1, v5, v7
	v_cvt_pk_bf16_f32 v5, v6, v8
	v_sub_f32_e32 v8, v2, v3
	v_mov_b32_e32 v2, v28
	v_mov_b32_e32 v3, v24
	v_pk_mul_f32 v[2:3], v[2:3], v[12:13]
	v_and_b32_e32 v7, 0xffff0000, v10
	v_and_b32_e32 v6, 0xffff0000, v14
	v_mov_b32_e32 v28, v25
	v_add_f32_e32 v9, v2, v3
	v_pk_mul_f32 v[2:3], v[28:29], v[6:7]
	v_mov_b32_e32 v24, v29
	v_sub_f32_e32 v2, v2, v3
	v_pk_mul_f32 v[6:7], v[24:25], v[6:7]
	v_cvt_pk_bf16_f32 v2, v8, v2
	v_lshlrev_b32_e32 v8, 16, v15
	v_add_f32_e32 v3, v6, v7
	v_cvt_pk_bf16_f32 v6, v9, v3
	v_lshlrev_b32_e32 v9, 16, v11
	v_mov_b32_e32 v12, v26
	v_mov_b32_e32 v13, v30
	v_pk_mul_f32 v[12:13], v[12:13], v[8:9]
	v_ashrrev_i32_e32 v20, 4, v40
	v_sub_f32_e32 v3, v12, v13
	v_mov_b32_e32 v12, v30
	v_mov_b32_e32 v13, v26
	v_pk_mul_f32 v[8:9], v[12:13], v[8:9]
	v_mov_b32_e32 v30, v27
	v_add_f32_e32 v7, v8, v9
	v_and_b32_e32 v9, 0xffff0000, v11
	v_and_b32_e32 v8, 0xffff0000, v15
	v_pk_mul_f32 v[10:11], v[30:31], v[8:9]
	v_mov_b32_e32 v26, v31
	v_sub_f32_e32 v10, v10, v11
	v_cvt_pk_bf16_f32 v3, v3, v10
	v_pk_mul_f32 v[8:9], v[26:27], v[8:9]
	v_lshlrev_b32_e32 v26, 3, v56
	v_add_f32_e32 v8, v8, v9
	v_cvt_pk_bf16_f32 v7, v7, v8
	ds_write_b128 v163, v[0:3] offset:1024
	ds_write_b128 v163, v[4:7] offset:3072
	v_and_b32_e32 v0, 0x78, v26
	v_ashrrev_i32_e32 v21, 31, v20
	v_lshlrev_b32_e32 v27, 1, v0
	v_lshlrev_b64 v[48:49], 12, v[20:21]
	v_or_b32_e32 v0, v48, v27
	v_mov_b32_e32 v1, v49
	s_waitcnt lgkmcnt(0)
	v_add_u32_e32 v22, 32, v20
	v_lshl_add_u64 v[52:53], s[16:17], 0, v[0:1]
	global_load_dwordx4 v[0:3], v[52:53], off offset:256
	v_ashrrev_i32_e32 v23, 31, v22
	v_lshlrev_b64 v[4:5], 12, v[22:23]
	v_or_b32_e32 v4, v4, v27
	v_ashrrev_i32_e32 v24, 3, v40
	v_lshl_add_u64 v[12:13], s[16:17], 0, v[4:5]
	s_add_u32 s16, s24, s48
	v_ashrrev_i32_e32 v25, 31, v24
	s_addc_u32 s17, s25, s49
	v_lshlrev_b64 v[50:51], 7, v[24:25]
	v_lshlrev_b32_e32 v18, 4, v56
	v_lshl_add_u64 v[16:17], s[16:17], 0, v[50:51]
	v_and_b32_e32 v96, 0x70, v18
	global_load_dwordx4 v[4:7], v[12:13], off offset:256
	global_load_dwordx4 v[8:11], v[52:53], off
	v_lshl_add_u64 v[54:55], v[16:17], 0, v[96:97]
	global_load_dwordx4 v[12:15], v[12:13], off
	v_and_b32_e32 v21, 0xfffff0, v20
	global_load_dwordx4 v[16:19], v[54:55], off
	v_lshlrev_b32_e32 v23, 1, v20
	v_and_or_b32 v21, v23, 8, v21
	v_lshrrev_b32_e32 v23, 1, v20
	v_lshrrev_b32_e32 v21, 1, v21
	v_bfe_u32 v25, v26, 5, 2
	v_and_b32_e32 v26, 3, v20
	v_or_b32_e32 v21, v21, v25
	v_and_or_b32 v23, v23, 4, v26
	v_lshlrev_b32_e32 v21, 9, v21
	v_lshlrev_b32_e32 v23, 6, v23
	v_and_b32_e32 v26, 48, v27
	v_or3_b32 v21, v21, v23, v26
	v_and_b32_e32 v28, 0xfffff0, v22
	v_lshlrev_b32_e32 v29, 1, v22
	v_add_u32_e32 v166, 0, v21
	v_and_or_b32 v28, v29, 8, v28
	s_waitcnt vmcnt(0)
	v_lshrrev_b32_e32 v28, 1, v28
	v_or_b32_e32 v25, v28, v25
	v_lshlrev_b32_e32 v25, 9, v25
	v_or3_b32 v23, v25, v23, v26
	s_cmp_lg_u32 0, -1
	s_cselect_b32 s3, 0, 0
	v_add_u32_e32 v167, 0, v23
	s_add_i32 s12, 0, 0x10000
	v_bitop3_b32 v178, v130, v63, v96 bitop3:0xde
	v_add_u32_e32 v179, s12, v178
	v_bitop3_b32 v180, v58, v63, v96 bitop3:0xde
	v_add_u32_e32 v181, s12, v180
	v_bitop3_b32 v182, v59, v63, v96 bitop3:0xde
	v_add_u32_e32 v183, s12, v182
	v_bitop3_b32 v184, v62, v63, v96 bitop3:0xde
	v_add_u32_e32 v185, s12, v184
	s_lshl_b32 s27, s2, 2
	s_mov_b32 s2, 0x40000
	s_mov_b64 s[16:17], 0x40000
	v_add_co_u32_e32 v66, vcc, s2, v52
	s_mov_b32 s2, 0x60000
	s_nop 0
	v_addc_co_u32_e32 v67, vcc, 0, v53, vcc
	s_add_i32 s10, s27, 4
	s_add_i32 s27, s27, s28
	s_waitcnt vmcnt(4)
	ds_write_b128 v166, v[0:3]
	v_lshlrev_b32_e32 v0, 8, v20
	v_and_b32_e32 v1, 0x70, v40
	v_bitop3_b32 v0, v27, v0, v1 bitop3:0xde
	v_add_u32_e32 v168, 0, v0
	v_lshlrev_b32_e32 v0, 8, v22
	v_bitop3_b32 v0, v0, v27, v1 bitop3:0xf6
	v_lshlrev_b32_e32 v1, 4, v24
	v_add_u32_e32 v169, 0, v0
	v_lshlrev_b32_e32 v0, 7, v24
	v_and_b32_e32 v1, 0x70, v1
	v_bitop3_b32 v75, v1, v0, v96 bitop3:0xde
	s_waitcnt vmcnt(3)
	ds_write_b128 v167, v[4:7]
	s_waitcnt vmcnt(2)
	ds_write_b128 v168, v[8:11] offset:32768
	v_add_u32_e32 v0, s12, v75
	v_lshlrev_b32_e32 v8, 8, v158
	s_waitcnt vmcnt(1)
	ds_write_b128 v169, v[12:15] offset:32768
	s_waitcnt vmcnt(0)
	ds_write_b128 v0, v[16:19]
	v_bitop3_b32 v0, v130, v8, v96 bitop3:0xde
	v_add_u32_e32 v170, 0, v0
	s_waitcnt lgkmcnt(0)
	s_barrier
	ds_read_b128 v[0:3], v170 offset:32768
	ds_read_b128 v[4:7], v170 offset:40960
	s_waitcnt lgkmcnt(1)
	v_mfma_f32_32x32x16_bf16 v[32:47], v[0:3], v[126:129], 0
	v_bitop3_b32 v0, v58, v8, v96 bitop3:0xde
	v_add_u32_e32 v171, 0, v0
	v_add_u32_e32 v187, 0, v75
	v_add_u32_e32 v188, 0x12000, v187
	s_waitcnt lgkmcnt(0)
	v_mfma_f32_32x32x16_bf16 v[16:31], v[4:7], v[126:129], 0
	ds_read_b128 v[0:3], v171 offset:32768
	ds_read_b128 v[4:7], v171 offset:40960
	s_waitcnt lgkmcnt(1)
	v_mfma_f32_32x32x16_bf16 v[32:47], v[0:3], v[122:125], v[32:47]
	v_bitop3_b32 v0, v59, v8, v96 bitop3:0xde
	v_add_u32_e32 v172, 0, v0
	s_waitcnt lgkmcnt(0)
	v_mfma_f32_32x32x16_bf16 v[16:31], v[4:7], v[122:125], v[16:31]
	ds_read_b128 v[0:3], v172 offset:32768
	ds_read_b128 v[4:7], v172 offset:40960
	s_waitcnt lgkmcnt(1)
	v_mfma_f32_32x32x16_bf16 v[32:47], v[0:3], v[118:121], v[32:47]
	v_bitop3_b32 v0, v62, v8, v96 bitop3:0xde
	v_add_u32_e32 v173, 0, v0
	s_waitcnt lgkmcnt(0)
	v_mfma_f32_32x32x16_bf16 v[16:31], v[4:7], v[118:121], v[16:31]
	ds_read_b128 v[0:3], v173 offset:32768
	ds_read_b128 v[4:7], v173 offset:40960
	s_waitcnt lgkmcnt(1)
	v_mfma_f32_32x32x16_bf16 v[32:47], v[0:3], v[114:117], v[32:47]
	v_or_b32_e32 v0, 0x80, v130
	v_bitop3_b32 v0, v0, v8, v96 bitop3:0xde
	v_add_u32_e32 v174, 0, v0
	s_waitcnt lgkmcnt(0)
	v_mfma_f32_32x32x16_bf16 v[16:31], v[4:7], v[114:117], v[16:31]
	ds_read_b128 v[0:3], v174 offset:32768
	ds_read_b128 v[4:7], v174 offset:40960
	s_waitcnt lgkmcnt(1)
	v_mfma_f32_32x32x16_bf16 v[32:47], v[0:3], v[110:113], v[32:47]
	v_or_b32_e32 v0, 0xa0, v130
	v_bitop3_b32 v0, v0, v8, v96 bitop3:0xde
	v_add_u32_e32 v175, 0, v0
	s_waitcnt lgkmcnt(0)
	v_mfma_f32_32x32x16_bf16 v[16:31], v[4:7], v[110:113], v[16:31]
	ds_read_b128 v[0:3], v175 offset:32768
	ds_read_b128 v[4:7], v175 offset:40960
	s_waitcnt lgkmcnt(1)
	v_mfma_f32_32x32x16_bf16 v[32:47], v[0:3], v[106:109], v[32:47]
	v_or_b32_e32 v0, 0xc0, v130
	v_bitop3_b32 v0, v0, v8, v96 bitop3:0xde
	v_add_u32_e32 v176, 0, v0
	s_waitcnt lgkmcnt(0)
	v_mfma_f32_32x32x16_bf16 v[16:31], v[4:7], v[106:109], v[16:31]
	ds_read_b128 v[0:3], v176 offset:32768
	ds_read_b128 v[4:7], v176 offset:40960
	s_waitcnt lgkmcnt(1)
	v_mfma_f32_32x32x16_bf16 v[32:47], v[0:3], v[102:105], v[32:47]
	v_or_b32_e32 v0, 0xe0, v130
	v_bitop3_b32 v0, v0, v8, v96 bitop3:0xde
	v_add_u32_e32 v177, 0, v0
	s_waitcnt lgkmcnt(0)
	v_mfma_f32_32x32x16_bf16 v[16:31], v[4:7], v[102:105], v[16:31]
	ds_read_b128 v[0:3], v177 offset:32768
	ds_read_b128 v[4:7], v177 offset:40960
	s_waitcnt lgkmcnt(1)
	v_mfma_f32_32x32x16_bf16 v[32:47], v[0:3], v[98:101], v[32:47]
	s_waitcnt lgkmcnt(0)
	v_mfma_f32_32x32x16_bf16 v[16:31], v[4:7], v[98:101], v[16:31]
	ds_read_b128 v[0:3], v179
	ds_read_b128 v[4:7], v163
	ds_read_b128 v[8:11], v179 offset:4096
	ds_read_b128 v[12:15], v163 offset:1024
	s_waitcnt lgkmcnt(2)
	v_mfma_f32_32x32x16_bf16 v[32:47], v[0:3], v[4:7], v[32:47]
	ds_read_b128 v[0:3], v181
	s_waitcnt lgkmcnt(2)
	v_mfma_f32_32x32x16_bf16 v[16:31], v[8:11], v[4:7], v[16:31]
	v_lshlrev_b32_e32 v8, 3, v131
	v_and_b32_e32 v4, 0xc0, v57
	v_and_or_b32 v9, v8, 24, v4
	ds_read_b128 v[4:7], v181 offset:4096
	s_waitcnt lgkmcnt(0)
	v_mfma_f32_32x32x16_bf16 v[16:31], v[4:7], v[12:15], v[16:31]
	ds_read_b128 v[4:7], v163 offset:2048
	v_mfma_f32_32x32x16_bf16 v[32:47], v[0:3], v[12:15], v[32:47]
	v_lshlrev_b32_e32 v0, 1, v56
	v_and_b32_e32 v0, 32, v0
	v_and_b32_e32 v1, 0x100, v8
	v_or3_b32 v57, v9, v0, v1
	ds_read_b128 v[0:3], v183
	ds_read_b128 v[8:11], v183 offset:4096
	ds_read_b128 v[58:61], v163 offset:3072
	ds_read_b128 v[62:65], v185 offset:4096
	s_waitcnt lgkmcnt(3)
	v_mfma_f32_32x32x16_bf16 v[32:47], v[0:3], v[4:7], v[32:47]
	ds_read_b128 v[0:3], v185
	v_add_u32_e32 v164, s3, v57
	s_waitcnt lgkmcnt(3)
	v_mfma_f32_32x32x16_bf16 v[16:31], v[8:11], v[4:7], v[16:31]
	s_waitcnt lgkmcnt(0)
	v_mfma_f32_32x32x16_bf16 v[32:47], v[0:3], v[58:61], v[32:47]
	v_mov_b64_e32 v[0:1], s[80:81]
	v_mov_b64_e32 v[14:15], s[94:95]
	v_mov_b64_e32 v[2:3], s[82:83]
	v_mov_b64_e32 v[4:5], s[84:85]
	v_mov_b64_e32 v[6:7], s[86:87]
	v_mov_b64_e32 v[8:9], s[88:89]
	v_mov_b64_e32 v[10:11], s[90:91]
	v_mfma_f32_32x32x16_bf16 v[16:31], v[62:65], v[58:61], v[16:31]
	s_nop 3
	v_max_f32_e32 v58, v33, v33
	v_max_f32_e32 v59, v32, v32
	v_max_f32_e32 v58, v59, v58
	v_max3_f32 v74, v58, v34, v35
	v_lshl_add_u64 v[58:59], v[52:53], 0, s[16:17]
	s_mov_b64 s[16:17], 0x60000
	v_lshl_add_u64 v[62:63], v[52:53], 0, s[16:17]
	v_add_co_u32_e32 v52, vcc, s2, v52
	s_movk_i32 s2, 0x2000
	s_nop 0
	v_addc_co_u32_e32 v53, vcc, 0, v53, vcc
	global_load_dwordx4 v[58:61], v[58:59], off offset:256
	s_nop 0
	global_load_dwordx4 v[62:65], v[62:63], off offset:256
	s_nop 0
	global_load_dwordx4 v[66:69], v[66:67], off
	s_nop 0
	global_load_dwordx4 v[70:73], v[52:53], off
	v_add_co_u32_e32 v52, vcc, s2, v54
	v_max3_f32 v74, v74, v36, v37
	s_nop 0
	v_addc_co_u32_e32 v53, vcc, 0, v55, vcc
	global_load_dwordx4 v[52:55], v[52:53], off
	v_max3_f32 v74, v74, v38, v39
	v_max3_f32 v74, v74, v40, v41
	v_max3_f32 v74, v74, v42, v43
	v_max3_f32 v74, v74, v44, v45
	v_max3_f32 v74, v74, v46, v47
	v_max3_f32 v74, v74, v16, v17
	v_max3_f32 v74, v74, v18, v19
	v_max3_f32 v74, v74, v20, v21
	v_max3_f32 v74, v74, v22, v23
	v_max3_f32 v74, v74, v24, v25
	v_max3_f32 v74, v74, v26, v27
	v_max3_f32 v74, v74, v28, v29
	v_max3_f32 v74, v74, v30, v31
	v_mov_b32_e32 v76, v74
	s_nop 1
	v_permlane32_swap_b32_e32 v74, v76
	v_max_f32_e32 v76, v76, v76
	v_max_f32_e32 v74, v74, v74
	v_max_f32_e32 v74, v74, v76
	v_add_f32_e32 v76, 0x7149f2ca, v74
	v_max_f32_e32 v74, 0xf149f2ca, v74
	v_cmp_ge_f32_e32 vcc, s21, v76
	v_sub_f32_e32 v76, 0xf149f2ca, v74
	v_mul_f32_e32 v76, 0x3dd53b94, v76
	v_exp_f32_e32 v76, v76
	s_cmp_eq_u64 vcc, exec
	s_cselect_b64 vcc, -1, 0
	v_cndmask_b32_e32 v165, v74, v207, vcc
	v_mul_f32_e32 v74, 0xbdd53b94, v165
	s_addk_i32 s3, 0x4000
	v_cndmask_b32_e64 v186, v76, 1.0, vcc
	v_mov_b32_e32 v76, v74
	v_pk_fma_f32 v[148:149], v[16:17], s[74:75], v[74:75] op_sel_hi:[1,0,0]
	v_add_u32_e32 v162, s3, v57
	v_and_b32_e32 v16, 7, v56
	v_readlane_b32 s2, v253, 11
	v_fmamk_f32 v32, v32, 0x3dd53b94, v74
	v_fmamk_f32 v33, v33, 0x3dd53b94, v74
	v_fmamk_f32 v34, v34, 0x3dd53b94, v74
	v_fmamk_f32 v35, v35, 0x3dd53b94, v74
	v_fmamk_f32 v36, v36, 0x3dd53b94, v74
	v_fmamk_f32 v37, v37, 0x3dd53b94, v74
	v_fmamk_f32 v38, v38, 0x3dd53b94, v74
	v_fmamk_f32 v39, v39, 0x3dd53b94, v74
	v_fmamk_f32 v40, v40, 0x3dd53b94, v74
	v_fmamk_f32 v41, v41, 0x3dd53b94, v74
	v_fmamk_f32 v42, v42, 0x3dd53b94, v74
	v_fmamk_f32 v43, v43, 0x3dd53b94, v74
	v_fmamk_f32 v44, v44, 0x3dd53b94, v74
	v_fmamk_f32 v45, v45, 0x3dd53b94, v74
	v_fmamk_f32 v46, v46, 0x3dd53b94, v74
	v_fmac_f32_e32 v76, 0x3dd53b94, v47
	v_lshl_or_b32 v50, v16, 4, v50
	v_readlane_b32 s3, v253, 12
	v_exp_f32_e32 v220, v32
	v_exp_f32_e32 v222, v33
	v_exp_f32_e32 v218, v34
	v_exp_f32_e32 v221, v35
	v_exp_f32_e32 v216, v36
	v_exp_f32_e32 v219, v37
	v_exp_f32_e32 v215, v38
	v_exp_f32_e32 v217, v39
	v_exp_f32_e32 v212, v40
	v_exp_f32_e32 v214, v41
	v_exp_f32_e32 v210, v42
	v_exp_f32_e32 v213, v43
	v_exp_f32_e32 v198, v44
	v_exp_f32_e32 v211, v45
	v_exp_f32_e32 v197, v46
	v_exp_f32_e32 v199, v76
	v_lshl_add_u64 v[132:133], s[2:3], 0, v[50:51]
	v_and_b32_e32 v16, 15, v56
	v_readlane_b32 s2, v253, 15
	s_waitcnt vmcnt(0)
	v_lshl_or_b32 v48, v16, 4, v48
	v_readlane_b32 s3, v253, 16
	v_mov_b64_e32 v[12:13], s[92:93]
	v_readlane_b32 s88, v254, 6
	v_readlane_b32 s90, v254, 4
	v_readlane_b32 s86, v254, 2
	v_readlane_b32 s92, v253, 57
	v_pk_fma_f32 v[142:143], v[30:31], s[74:75], v[74:75] op_sel_hi:[1,0,0]
	v_pk_fma_f32 v[150:151], v[28:29], s[74:75], v[74:75] op_sel_hi:[1,0,0]
	v_pk_fma_f32 v[152:153], v[26:27], s[74:75], v[74:75] op_sel_hi:[1,0,0]
	v_pk_fma_f32 v[138:139], v[24:25], s[74:75], v[74:75] op_sel_hi:[1,0,0]
	v_pk_fma_f32 v[140:141], v[22:23], s[74:75], v[74:75] op_sel_hi:[1,0,0]
	v_pk_fma_f32 v[144:145], v[20:21], s[74:75], v[74:75] op_sel_hi:[1,0,0]
	v_pk_fma_f32 v[146:147], v[18:19], s[74:75], v[74:75] op_sel_hi:[1,0,0]
	s_waitcnt vmcnt(4)
	ds_write_b128 v166, v[58:61] offset:16384
	s_waitcnt vmcnt(3)
	ds_write_b128 v167, v[62:65] offset:16384
	s_waitcnt vmcnt(2)
	ds_write_b128 v168, v[66:69] offset:49152
	s_waitcnt vmcnt(1)
	ds_write_b128 v169, v[70:73] offset:49152
	s_waitcnt vmcnt(0)
	ds_write_b128 v188, v[52:55]
	v_lshl_add_u64 v[134:135], s[2:3], 0, v[48:49]
	v_mov_b64_e32 v[62:63], v[14:15]
	v_mov_b64_e32 v[46:47], v[14:15]
	v_mov_b64_e32 v[30:31], v[14:15]
	s_mov_b64 s[82:83], 0x5000
	s_movk_i32 s85, 0x3000
	s_mov_b32 s84, 0x18000
	v_readlane_b32 s94, v254, 10
	v_readlane_b32 s89, v254, 7
	v_readlane_b32 s91, v254, 5
	v_readlane_b32 s87, v254, 3
	v_readlane_b32 s93, v253, 58
	v_readlane_b32 s95, v253, 54
	v_mov_b64_e32 v[60:61], v[12:13]
	v_mov_b64_e32 v[58:59], v[10:11]
	v_mov_b64_e32 v[56:57], v[8:9]
	v_mov_b64_e32 v[54:55], v[6:7]
	v_mov_b64_e32 v[52:53], v[4:5]
	v_mov_b64_e32 v[50:51], v[2:3]
	v_mov_b64_e32 v[48:49], v[0:1]
	v_mov_b64_e32 v[44:45], v[12:13]
	v_mov_b64_e32 v[42:43], v[10:11]
	v_mov_b64_e32 v[40:41], v[8:9]
	v_mov_b64_e32 v[38:39], v[6:7]
	v_mov_b64_e32 v[36:37], v[4:5]
	v_mov_b64_e32 v[34:35], v[2:3]
	v_mov_b64_e32 v[32:33], v[0:1]
	v_mov_b64_e32 v[28:29], v[12:13]
	v_mov_b64_e32 v[26:27], v[10:11]
	v_mov_b64_e32 v[24:25], v[8:9]
	v_mov_b64_e32 v[22:23], v[6:7]
	v_mov_b64_e32 v[20:21], v[4:5]
	v_mov_b64_e32 v[18:19], v[2:3]
	v_mov_b64_e32 v[16:17], v[0:1]
	s_waitcnt lgkmcnt(0)
	s_barrier
	v_mbcnt_lo_u32_b32 v64, -1, 0
	v_mbcnt_hi_u32_b32 v64, -1, v64
	s_and_b32 s2, s78, 1
	s_lshl_b32 s3, s2, 2
	v_lshrrev_b32_e32 v65, 4, v64
	v_and_b32_e32 v66, 15, v64
	v_add_u32_e32 v67, s3, v65
	v_xor_b32_e32 v66, v66, v67
	v_lshlrev_b32_e32 v66, 4, v66
	v_lshl_add_u32 v166, v65, 12, v66
	v_lshrrev_b32_e32 v65, 3, v64
	v_and_b32_e32 v66, 7, v64
	v_xor_b32_e32 v66, v66, v65
	v_lshlrev_b32_e32 v66, 4, v66
	v_lshl_add_u32 v168, v65, 7, v66
	v_bfe_u32 v65, v64, 4, 1
	v_bfe_u32 v66, v64, 2, 2
	v_lshl_add_u32 v65, v65, 3, v66
	v_lshrrev_b32_e32 v66, 5, v64
	v_and_b32_e32 v67, 3, v64
	v_lshlrev_b32_e32 v67, 4, v67
	v_lshl_add_u32 v66, v66, 6, v67
	v_lshl_add_u32 v167, v65, 12, v66
	s_bfe_u32 s2, s78, 0x10002
	s_lshl_b32 s2, s2, 16
	s_bfe_u32 s3, s78, 0x10001
	s_lshl_b32 s3, s3, 14
	s_add_u32 s2, s2, s3
	s_and_b32 s3, s78, 1
	s_lshl_b32 s3, s3, 7
	s_add_u32 s2, s2, s3
	v_add_u32_e32 v167, s2, v167
	.p2align 7

.LBB0_751:
	v_max_f32_e32 v84, v84, v84
	v_max_f32_e32 v85, v165, v165
	v_max_f32_e32 v84, v85, v84
	v_sub_f32_e32 v85, v165, v84
	v_mul_f32_e32 v85, 0x3dd53b94, v85
	v_exp_f32_e32 v195, v85
	v_mul_f32_e32 v136, 0xbdd53b94, v84
	v_mov_b32_e32 v165, v84
	s_branch .LBB0_744
	.p2align 7

.LBB0_1037:
	s_ashr_i32 s53, s52, 31
	s_lshl_b64 s[34:35], s[52:53], 20
	s_add_u32 s68, s50, s34
	s_addc_u32 s69, s51, s35
	s_and_b64 s[34:35], s[42:43], exec
	s_cselect_b32 s10, s69, s45
	s_cselect_b32 s12, s68, s44
	s_ashr_i32 s31, s30, 31
	s_lshl_b64 s[34:35], s[30:31], 20
	s_add_u32 s82, s46, s34
	s_addc_u32 s83, s47, s35
	s_and_b64 s[34:35], s[42:43], exec
	s_cselect_b32 s18, s83, s85
	s_cselect_b32 s20, s82, s84
	s_add_u32 s44, s44, 0x80080
	s_addc_u32 s45, s45, 0
	s_add_u32 s28, s84, 0x100
	v_mov_b32_e32 v0, 0
	s_addc_u32 s31, s85, 0
	s_mov_b32 s33, -2
	v_mov_b32_e32 v1, v0
	v_mov_b32_e32 v2, v0
	v_mov_b32_e32 v3, v0
	v_mov_b32_e32 v4, v0
	v_mov_b32_e32 v5, v0
	v_mov_b32_e32 v6, v0
	v_mov_b32_e32 v7, v0
	v_mov_b32_e32 v16, v0
	v_mov_b32_e32 v17, v0
	v_mov_b32_e32 v18, v0
	v_mov_b32_e32 v19, v0
	v_mov_b32_e32 v20, v0
	v_mov_b32_e32 v21, v0
	v_mov_b32_e32 v22, v0
	v_mov_b32_e32 v23, v0
	v_mov_b32_e32 v32, v0
	v_mov_b32_e32 v33, v0
	v_mov_b32_e32 v34, v0
	v_mov_b32_e32 v35, v0
	v_mov_b32_e32 v36, v0
	v_mov_b32_e32 v37, v0
	v_mov_b32_e32 v38, v0
	v_mov_b32_e32 v39, v0
	v_mov_b32_e32 v48, v0
	v_mov_b32_e32 v49, v0
	v_mov_b32_e32 v50, v0
	v_mov_b32_e32 v51, v0
	v_mov_b32_e32 v52, v0
	v_mov_b32_e32 v53, v0
	v_mov_b32_e32 v54, v0
	v_mov_b32_e32 v55, v0
	v_mov_b32_e32 v8, v0
	v_mov_b32_e32 v9, v0
	v_mov_b32_e32 v10, v0
	v_mov_b32_e32 v11, v0
	v_mov_b32_e32 v12, v0
	v_mov_b32_e32 v13, v0
	v_mov_b32_e32 v14, v0
	v_mov_b32_e32 v15, v0
	v_mov_b32_e32 v24, v0
	v_mov_b32_e32 v25, v0
	v_mov_b32_e32 v26, v0
	v_mov_b32_e32 v27, v0
	v_mov_b32_e32 v28, v0
	v_mov_b32_e32 v29, v0
	v_mov_b32_e32 v30, v0
	v_mov_b32_e32 v31, v0
	v_mov_b32_e32 v40, v0
	v_mov_b32_e32 v41, v0
	v_mov_b32_e32 v42, v0
	v_mov_b32_e32 v43, v0
	v_mov_b32_e32 v44, v0
	v_mov_b32_e32 v45, v0
	v_mov_b32_e32 v46, v0
	v_mov_b32_e32 v47, v0
	v_mov_b32_e32 v56, v0
	v_mov_b32_e32 v57, v0
	v_mov_b32_e32 v58, v0
	v_mov_b32_e32 v59, v0
	v_mov_b32_e32 v60, v0
	v_mov_b32_e32 v61, v0
	v_mov_b32_e32 v62, v0
	v_mov_b32_e32 v63, v0
	v_mov_b32_e32 v64, v0
	v_mov_b32_e32 v65, v0
	v_mov_b32_e32 v66, v0
	v_mov_b32_e32 v67, v0
	v_mov_b32_e32 v68, v0
	v_mov_b32_e32 v69, v0
	v_mov_b32_e32 v70, v0
	v_mov_b32_e32 v71, v0
	v_mov_b32_e32 v80, v0
	v_mov_b32_e32 v81, v0
	v_mov_b32_e32 v82, v0
	v_mov_b32_e32 v83, v0
	v_mov_b32_e32 v84, v0
	v_mov_b32_e32 v85, v0
	v_mov_b32_e32 v86, v0
	v_mov_b32_e32 v87, v0
	v_mov_b32_e32 v98, v0
	v_mov_b32_e32 v99, v0
	v_mov_b32_e32 v100, v0
	v_mov_b32_e32 v101, v0
	v_mov_b32_e32 v102, v0
	v_mov_b32_e32 v103, v0
	v_mov_b32_e32 v104, v0
	v_mov_b32_e32 v105, v0
	v_mov_b32_e32 v114, v0
	v_mov_b32_e32 v115, v0
	v_mov_b32_e32 v116, v0
	v_mov_b32_e32 v117, v0
	v_mov_b32_e32 v118, v0
	v_mov_b32_e32 v119, v0
	v_mov_b32_e32 v120, v0
	v_mov_b32_e32 v121, v0
	v_mov_b32_e32 v72, v0
	v_mov_b32_e32 v73, v0
	v_mov_b32_e32 v74, v0
	v_mov_b32_e32 v75, v0
	v_mov_b32_e32 v76, v0
	v_mov_b32_e32 v77, v0
	v_mov_b32_e32 v78, v0
	v_mov_b32_e32 v79, v0
	v_mov_b32_e32 v88, v0
	v_mov_b32_e32 v89, v0
	v_mov_b32_e32 v90, v0
	v_mov_b32_e32 v91, v0
	v_mov_b32_e32 v92, v0
	v_mov_b32_e32 v93, v0
	v_mov_b32_e32 v94, v0
	v_mov_b32_e32 v95, v0
	v_mov_b32_e32 v106, v0
	v_mov_b32_e32 v107, v0
	v_mov_b32_e32 v108, v0
	v_mov_b32_e32 v109, v0
	v_mov_b32_e32 v110, v0
	v_mov_b32_e32 v111, v0
	v_mov_b32_e32 v112, v0
	v_mov_b32_e32 v113, v0
	v_mov_b32_e32 v122, v0
	v_mov_b32_e32 v123, v0
	v_mov_b32_e32 v124, v0
	v_mov_b32_e32 v125, v0
	v_mov_b32_e32 v126, v0
	v_mov_b32_e32 v127, v0
	v_mov_b32_e32 v128, v0
	v_mov_b32_e32 v129, v0
	v_add_u32_e32 v165, 0x80, v96
	v_add_u32_e32 v223, 0x80, v142
	v_add_u32_e32 v225, 0x80, v146
	v_add_u32_e32 v227, 0x80, v144
	.p2align 7

.LBB0_1264:
	s_ashr_i32 s17, s16, 31
	s_lshl_b64 s[24:25], s[16:17], 22
	s_add_u32 s24, s51, s24
	s_addc_u32 s25, s58, s25
	s_and_b64 s[30:31], s[40:41], exec
	s_cselect_b32 s12, s25, s43
	s_cselect_b32 s17, s24, s42
	s_ashr_i32 s5, s4, 31
	s_lshl_b64 s[30:31], s[4:5], 22
	s_add_u32 s30, s27, s30
	s_addc_u32 s31, s50, s31
	s_and_b64 s[52:53], s[40:41], exec
	s_cselect_b32 s5, s31, s45
	s_cselect_b32 s18, s30, s44
	s_add_u32 s42, s42, 0x200080
	s_addc_u32 s43, s43, 0
	s_add_u32 s20, s44, 0x100
	v_mov_b32_e32 v0, 0
	s_addc_u32 s28, s45, 0
	s_mov_b32 s33, -2
	v_mov_b32_e32 v1, v0
	v_mov_b32_e32 v2, v0
	v_mov_b32_e32 v3, v0
	v_mov_b32_e32 v4, v0
	v_mov_b32_e32 v5, v0
	v_mov_b32_e32 v6, v0
	v_mov_b32_e32 v7, v0
	v_mov_b32_e32 v16, v0
	v_mov_b32_e32 v17, v0
	v_mov_b32_e32 v18, v0
	v_mov_b32_e32 v19, v0
	v_mov_b32_e32 v20, v0
	v_mov_b32_e32 v21, v0
	v_mov_b32_e32 v22, v0
	v_mov_b32_e32 v23, v0
	v_mov_b32_e32 v32, v0
	v_mov_b32_e32 v33, v0
	v_mov_b32_e32 v34, v0
	v_mov_b32_e32 v35, v0
	v_mov_b32_e32 v36, v0
	v_mov_b32_e32 v37, v0
	v_mov_b32_e32 v38, v0
	v_mov_b32_e32 v39, v0
	v_mov_b32_e32 v48, v0
	v_mov_b32_e32 v49, v0
	v_mov_b32_e32 v50, v0
	v_mov_b32_e32 v51, v0
	v_mov_b32_e32 v52, v0
	v_mov_b32_e32 v53, v0
	v_mov_b32_e32 v54, v0
	v_mov_b32_e32 v55, v0
	v_mov_b32_e32 v8, v0
	v_mov_b32_e32 v9, v0
	v_mov_b32_e32 v10, v0
	v_mov_b32_e32 v11, v0
	v_mov_b32_e32 v12, v0
	v_mov_b32_e32 v13, v0
	v_mov_b32_e32 v14, v0
	v_mov_b32_e32 v15, v0
	v_mov_b32_e32 v24, v0
	v_mov_b32_e32 v25, v0
	v_mov_b32_e32 v26, v0
	v_mov_b32_e32 v27, v0
	v_mov_b32_e32 v28, v0
	v_mov_b32_e32 v29, v0
	v_mov_b32_e32 v30, v0
	v_mov_b32_e32 v31, v0
	v_mov_b32_e32 v40, v0
	v_mov_b32_e32 v41, v0
	v_mov_b32_e32 v42, v0
	v_mov_b32_e32 v43, v0
	v_mov_b32_e32 v44, v0
	v_mov_b32_e32 v45, v0
	v_mov_b32_e32 v46, v0
	v_mov_b32_e32 v47, v0
	v_mov_b32_e32 v56, v0
	v_mov_b32_e32 v57, v0
	v_mov_b32_e32 v58, v0
	v_mov_b32_e32 v59, v0
	v_mov_b32_e32 v60, v0
	v_mov_b32_e32 v61, v0
	v_mov_b32_e32 v62, v0
	v_mov_b32_e32 v63, v0
	v_mov_b32_e32 v64, v0
	v_mov_b32_e32 v65, v0
	v_mov_b32_e32 v66, v0
	v_mov_b32_e32 v67, v0
	v_mov_b32_e32 v68, v0
	v_mov_b32_e32 v69, v0
	v_mov_b32_e32 v70, v0
	v_mov_b32_e32 v71, v0
	v_mov_b32_e32 v80, v0
	v_mov_b32_e32 v81, v0
	v_mov_b32_e32 v82, v0
	v_mov_b32_e32 v83, v0
	v_mov_b32_e32 v84, v0
	v_mov_b32_e32 v85, v0
	v_mov_b32_e32 v86, v0
	v_mov_b32_e32 v87, v0
	v_mov_b32_e32 v98, v0
	v_mov_b32_e32 v99, v0
	v_mov_b32_e32 v100, v0
	v_mov_b32_e32 v101, v0
	v_mov_b32_e32 v102, v0
	v_mov_b32_e32 v103, v0
	v_mov_b32_e32 v104, v0
	v_mov_b32_e32 v105, v0
	v_mov_b32_e32 v114, v0
	v_mov_b32_e32 v115, v0
	v_mov_b32_e32 v116, v0
	v_mov_b32_e32 v117, v0
	v_mov_b32_e32 v118, v0
	v_mov_b32_e32 v119, v0
	v_mov_b32_e32 v120, v0
	v_mov_b32_e32 v121, v0
	v_mov_b32_e32 v72, v0
	v_mov_b32_e32 v73, v0
	v_mov_b32_e32 v74, v0
	v_mov_b32_e32 v75, v0
	v_mov_b32_e32 v76, v0
	v_mov_b32_e32 v77, v0
	v_mov_b32_e32 v78, v0
	v_mov_b32_e32 v79, v0
	v_mov_b32_e32 v88, v0
	v_mov_b32_e32 v89, v0
	v_mov_b32_e32 v90, v0
	v_mov_b32_e32 v91, v0
	v_mov_b32_e32 v92, v0
	v_mov_b32_e32 v93, v0
	v_mov_b32_e32 v94, v0
	v_mov_b32_e32 v95, v0
	v_mov_b32_e32 v106, v0
	v_mov_b32_e32 v107, v0
	v_mov_b32_e32 v108, v0
	v_mov_b32_e32 v109, v0
	v_mov_b32_e32 v110, v0
	v_mov_b32_e32 v111, v0
	v_mov_b32_e32 v112, v0
	v_mov_b32_e32 v113, v0
	v_mov_b32_e32 v122, v0
	v_mov_b32_e32 v123, v0
	v_mov_b32_e32 v124, v0
	v_mov_b32_e32 v125, v0
	v_mov_b32_e32 v126, v0
	v_mov_b32_e32 v127, v0
	v_mov_b32_e32 v128, v0
	v_mov_b32_e32 v129, v0
	v_add_u32_e32 v222, 0x80, v96
	v_add_u32_e32 v223, 0x80, v134
	v_add_u32_e32 v224, 0x80, v138
	v_add_u32_e32 v225, 0x80, v136
	v_add_u32_e32 v226, 0x200000, v138
	v_add_u32_e32 v227, 0x200000, v136
	.p2align 7

.LBB0_1283:
	s_ashr_i32 s25, s24, 31
	s_lshl_b64 s[30:31], s[24:25], 20
	s_add_u32 s30, s10, s30
	s_addc_u32 s31, s27, s31
	s_and_b64 s[38:39], s[42:43], exec
	s_cselect_b32 s3, s31, s53
	s_cselect_b32 s12, s30, s52
	s_ashr_i32 s17, s16, 31
	s_lshl_b64 s[38:39], s[16:17], 20
	s_add_u32 s44, s14, s38
	s_addc_u32 s45, s26, s39
	s_and_b64 s[38:39], s[42:43], exec
	s_cselect_b32 s17, s45, s69
	s_cselect_b32 s18, s44, s68
	s_add_u32 s52, s52, 0x80080
	s_addc_u32 s53, s53, 0
	s_add_u32 s20, s68, 0x100
	v_mov_b32_e32 v0, 0
	s_addc_u32 s25, s69, 0
	s_mov_b32 s28, -2
	v_mov_b32_e32 v1, v0
	v_mov_b32_e32 v2, v0
	v_mov_b32_e32 v3, v0
	v_mov_b32_e32 v4, v0
	v_mov_b32_e32 v5, v0
	v_mov_b32_e32 v6, v0
	v_mov_b32_e32 v7, v0
	v_mov_b32_e32 v16, v0
	v_mov_b32_e32 v17, v0
	v_mov_b32_e32 v18, v0
	v_mov_b32_e32 v19, v0
	v_mov_b32_e32 v20, v0
	v_mov_b32_e32 v21, v0
	v_mov_b32_e32 v22, v0
	v_mov_b32_e32 v23, v0
	v_mov_b32_e32 v32, v0
	v_mov_b32_e32 v33, v0
	v_mov_b32_e32 v34, v0
	v_mov_b32_e32 v35, v0
	v_mov_b32_e32 v36, v0
	v_mov_b32_e32 v37, v0
	v_mov_b32_e32 v38, v0
	v_mov_b32_e32 v39, v0
	v_mov_b32_e32 v48, v0
	v_mov_b32_e32 v49, v0
	v_mov_b32_e32 v50, v0
	v_mov_b32_e32 v51, v0
	v_mov_b32_e32 v52, v0
	v_mov_b32_e32 v53, v0
	v_mov_b32_e32 v54, v0
	v_mov_b32_e32 v55, v0
	v_mov_b32_e32 v8, v0
	v_mov_b32_e32 v9, v0
	v_mov_b32_e32 v10, v0
	v_mov_b32_e32 v11, v0
	v_mov_b32_e32 v12, v0
	v_mov_b32_e32 v13, v0
	v_mov_b32_e32 v14, v0
	v_mov_b32_e32 v15, v0
	v_mov_b32_e32 v24, v0
	v_mov_b32_e32 v25, v0
	v_mov_b32_e32 v26, v0
	v_mov_b32_e32 v27, v0
	v_mov_b32_e32 v28, v0
	v_mov_b32_e32 v29, v0
	v_mov_b32_e32 v30, v0
	v_mov_b32_e32 v31, v0
	v_mov_b32_e32 v40, v0
	v_mov_b32_e32 v41, v0
	v_mov_b32_e32 v42, v0
	v_mov_b32_e32 v43, v0
	v_mov_b32_e32 v44, v0
	v_mov_b32_e32 v45, v0
	v_mov_b32_e32 v46, v0
	v_mov_b32_e32 v47, v0
	v_mov_b32_e32 v56, v0
	v_mov_b32_e32 v57, v0
	v_mov_b32_e32 v58, v0
	v_mov_b32_e32 v59, v0
	v_mov_b32_e32 v60, v0
	v_mov_b32_e32 v61, v0
	v_mov_b32_e32 v62, v0
	v_mov_b32_e32 v63, v0
	v_mov_b32_e32 v64, v0
	v_mov_b32_e32 v65, v0
	v_mov_b32_e32 v66, v0
	v_mov_b32_e32 v67, v0
	v_mov_b32_e32 v68, v0
	v_mov_b32_e32 v69, v0
	v_mov_b32_e32 v70, v0
	v_mov_b32_e32 v71, v0
	v_mov_b32_e32 v80, v0
	v_mov_b32_e32 v81, v0
	v_mov_b32_e32 v82, v0
	v_mov_b32_e32 v83, v0
	v_mov_b32_e32 v84, v0
	v_mov_b32_e32 v85, v0
	v_mov_b32_e32 v86, v0
	v_mov_b32_e32 v87, v0
	v_mov_b32_e32 v98, v0
	v_mov_b32_e32 v99, v0
	v_mov_b32_e32 v100, v0
	v_mov_b32_e32 v101, v0
	v_mov_b32_e32 v102, v0
	v_mov_b32_e32 v103, v0
	v_mov_b32_e32 v104, v0
	v_mov_b32_e32 v105, v0
	v_mov_b32_e32 v114, v0
	v_mov_b32_e32 v115, v0
	v_mov_b32_e32 v116, v0
	v_mov_b32_e32 v117, v0
	v_mov_b32_e32 v118, v0
	v_mov_b32_e32 v119, v0
	v_mov_b32_e32 v120, v0
	v_mov_b32_e32 v121, v0
	v_mov_b32_e32 v72, v0
	v_mov_b32_e32 v73, v0
	v_mov_b32_e32 v74, v0
	v_mov_b32_e32 v75, v0
	v_mov_b32_e32 v76, v0
	v_mov_b32_e32 v77, v0
	v_mov_b32_e32 v78, v0
	v_mov_b32_e32 v79, v0
	v_mov_b32_e32 v88, v0
	v_mov_b32_e32 v89, v0
	v_mov_b32_e32 v90, v0
	v_mov_b32_e32 v91, v0
	v_mov_b32_e32 v92, v0
	v_mov_b32_e32 v93, v0
	v_mov_b32_e32 v94, v0
	v_mov_b32_e32 v95, v0
	v_mov_b32_e32 v106, v0
	v_mov_b32_e32 v107, v0
	v_mov_b32_e32 v108, v0
	v_mov_b32_e32 v109, v0
	v_mov_b32_e32 v110, v0
	v_mov_b32_e32 v111, v0
	v_mov_b32_e32 v112, v0
	v_mov_b32_e32 v113, v0
	v_mov_b32_e32 v122, v0
	v_mov_b32_e32 v123, v0
	v_mov_b32_e32 v124, v0
	v_mov_b32_e32 v125, v0
	v_mov_b32_e32 v126, v0
	v_mov_b32_e32 v127, v0
	v_mov_b32_e32 v128, v0
	v_mov_b32_e32 v129, v0
	v_add_u32_e32 v145, 0x80, v96
	v_add_u32_e32 v199, 0x80, v134
	v_add_u32_e32 v227, 0x80, v138
	v_add_u32_e32 v229, 0x80, v136
	.p2align 7
